# mix1a conv item: pointwise-MFMA LDS fragment reads hoisted 3 waits ahead (21 of 28), on v33
# baseline (speedup 1.0000x reference)
.LBB0_540:
	ds_read_b128 v[92:95], v91
	v_add_u32_e32 v102, s0, v90
	s_addk_i32 s0, 0x420
	s_cmpk_eq_i32 s0, 0x1080
	s_waitcnt lgkmcnt(0)
	v_mul_f32_e32 v78, v92, v92
	v_mul_f32_e32 v96, v93, v93
	v_mul_f32_e32 v98, v94, v94
	v_mul_f32_e32 v100, v95, v95
	v_mov_b32_e32 v79, v92
	v_mov_b32_e32 v97, v93
	v_mov_b32_e32 v99, v94
	v_mov_b32_e32 v101, v95
	v_pk_add_f32 v[78:79], v[78:79], v[96:97]
	v_pk_add_f32 v[96:97], v[98:99], v[100:101]
	s_nop 0
	v_pk_add_f32 v[78:79], v[78:79], v[96:97]
	ds_bpermute_b32 v97, v84, v79
	ds_bpermute_b32 v96, v84, v78
	s_waitcnt lgkmcnt(0)
	v_pk_add_f32 v[78:79], v[78:79], v[96:97]
	ds_bpermute_b32 v97, v85, v79
	ds_bpermute_b32 v96, v85, v78
	s_waitcnt lgkmcnt(0)
	v_pk_add_f32 v[78:79], v[78:79], v[96:97]
	ds_bpermute_b32 v97, v86, v79
	ds_bpermute_b32 v96, v86, v78
	s_waitcnt lgkmcnt(0)
	v_pk_add_f32 v[78:79], v[78:79], v[96:97]
	ds_bpermute_b32 v97, v87, v79
	ds_bpermute_b32 v96, v87, v78
	s_waitcnt lgkmcnt(0)
	v_pk_add_f32 v[78:79], v[78:79], v[96:97]
	ds_bpermute_b32 v97, v88, v79
	ds_bpermute_b32 v96, v88, v78
	s_waitcnt lgkmcnt(0)
	v_pk_add_f32 v[78:79], v[78:79], v[96:97]
	ds_bpermute_b32 v97, v89, v79
	ds_bpermute_b32 v96, v89, v78
	s_waitcnt lgkmcnt(0)
	v_pk_add_f32 v[78:79], v[78:79], v[96:97]
	s_nop 0
	v_pk_mul_f32 v[78:79], v[78:79], s[62:63] op_sel_hi:[1,0]
	s_nop 0
	v_fma_f32 v78, -v79, v79, v78
	v_max_f32_e32 v78, 0, v78
	v_add_f32_e32 v78, 0x3727c5ac, v78
	v_cmp_gt_f32_e32 vcc, s35, v78
	v_mul_f32_e32 v96, 0x4b800000, v78
	v_sub_f32_e32 v95, v95, v79
	v_cndmask_b32_e32 v78, v78, v96, vcc
	v_rsq_f32_e32 v78, v78
	v_sub_f32_e32 v94, v94, v79
	v_sub_f32_e32 v93, v93, v79
	v_sub_f32_e32 v92, v92, v79
	v_mul_f32_e32 v96, 0x45800000, v78
	v_cndmask_b32_e32 v78, v78, v96, vcc
	v_pk_mul_f32 v[92:93], v[92:93], v[78:79] op_sel_hi:[1,0]
	v_pk_mul_f32 v[78:79], v[94:95], v[78:79] op_sel_hi:[1,0]
	s_waitcnt vmcnt(0)
	v_pk_fma_f32 v[94:95], v[68:69], v[78:79], v[72:73]
	v_pk_fma_f32 v[78:79], v[66:67], v[92:93], v[70:71]
	s_nop 0
	v_mul_f32_e32 v92, 0xbfb8aa3b, v78
	v_mul_f32_e32 v93, 0xbfb8aa3b, v79
	v_exp_f32_e32 v92, v92
	v_exp_f32_e32 v93, v93
	v_add_f32_e32 v92, 1.0, v92
	v_add_f32_e32 v93, 1.0, v93
	v_rcp_f32_e32 v92, v92
	v_rcp_f32_e32 v93, v93
	s_nop 0
	v_pk_mul_f32 v[78:79], v[78:79], v[92:93]
	s_nop 0
	v_cvt_pk_bf16_f32 v78, v78, v79
	v_mul_f32_e32 v79, 0xbfb8aa3b, v94
	v_exp_f32_e32 v79, v79
	s_nop 0
	v_add_f32_e32 v79, 1.0, v79
	v_rcp_f32_e32 v92, v79
	v_mul_f32_e32 v79, 0xbfb8aa3b, v95
	v_exp_f32_e32 v79, v79
	s_nop 0
	v_add_f32_e32 v79, 1.0, v79
	v_rcp_f32_e32 v93, v79
	s_nop 0
	v_pk_mul_f32 v[92:93], v[94:95], v[92:93]
	s_nop 0
	v_cvt_pk_bf16_f32 v79, v92, v93
	ds_write_b64 v102, v[78:79]
	ds_read_b128 v[92:95], v91 offset:1040
	v_add_u32_e32 v91, 0x820, v91
	s_waitcnt lgkmcnt(0)
	v_mul_f32_e32 v78, v92, v92
	v_mul_f32_e32 v96, v93, v93
	v_mul_f32_e32 v98, v94, v94
	v_mul_f32_e32 v100, v95, v95
	v_mov_b32_e32 v79, v92
	v_mov_b32_e32 v97, v93
	v_mov_b32_e32 v99, v94
	v_mov_b32_e32 v101, v95
	v_pk_add_f32 v[78:79], v[78:79], v[96:97]
	v_pk_add_f32 v[96:97], v[98:99], v[100:101]
	s_nop 0
	v_pk_add_f32 v[78:79], v[78:79], v[96:97]
	ds_bpermute_b32 v97, v84, v79
	ds_bpermute_b32 v96, v84, v78
	s_waitcnt lgkmcnt(0)
	v_pk_add_f32 v[78:79], v[78:79], v[96:97]
	ds_bpermute_b32 v97, v85, v79
	ds_bpermute_b32 v96, v85, v78
	s_waitcnt lgkmcnt(0)
	v_pk_add_f32 v[78:79], v[78:79], v[96:97]
	ds_bpermute_b32 v97, v86, v79
	ds_bpermute_b32 v96, v86, v78
	s_waitcnt lgkmcnt(0)
	v_pk_add_f32 v[78:79], v[78:79], v[96:97]
	ds_bpermute_b32 v97, v87, v79
	ds_bpermute_b32 v96, v87, v78
	s_waitcnt lgkmcnt(0)
	v_pk_add_f32 v[78:79], v[78:79], v[96:97]
	ds_bpermute_b32 v97, v88, v79
	ds_bpermute_b32 v96, v88, v78
	s_waitcnt lgkmcnt(0)
	v_pk_add_f32 v[78:79], v[78:79], v[96:97]
	ds_bpermute_b32 v97, v89, v79
	ds_bpermute_b32 v96, v89, v78
	s_waitcnt lgkmcnt(0)
	v_pk_add_f32 v[78:79], v[78:79], v[96:97]
	s_nop 0
	v_pk_mul_f32 v[78:79], v[78:79], s[62:63] op_sel_hi:[1,0]
	s_nop 0
	v_fma_f32 v78, -v79, v79, v78
	v_max_f32_e32 v78, 0, v78
	v_add_f32_e32 v78, 0x3727c5ac, v78
	v_cmp_gt_f32_e32 vcc, s35, v78
	v_mul_f32_e32 v96, 0x4b800000, v78
	v_sub_f32_e32 v93, v93, v79
	v_cndmask_b32_e32 v78, v78, v96, vcc
	v_rsq_f32_e32 v78, v78
	v_sub_f32_e32 v92, v92, v79
	v_sub_f32_e32 v95, v95, v79
	v_sub_f32_e32 v94, v94, v79
	v_mul_f32_e32 v96, 0x45800000, v78
	v_cndmask_b32_e32 v78, v78, v96, vcc
	v_pk_mul_f32 v[92:93], v[92:93], v[78:79] op_sel_hi:[1,0]
	v_pk_mul_f32 v[78:79], v[94:95], v[78:79] op_sel_hi:[1,0]
	v_pk_fma_f32 v[92:93], v[66:67], v[92:93], v[70:71]
	v_pk_fma_f32 v[78:79], v[68:69], v[78:79], v[72:73]
	v_mul_f32_e32 v94, 0xbfb8aa3b, v92
	v_mul_f32_e32 v95, 0xbfb8aa3b, v93
	v_exp_f32_e32 v94, v94
	v_exp_f32_e32 v95, v95
	v_add_f32_e32 v94, 1.0, v94
	v_add_f32_e32 v95, 1.0, v95
	v_rcp_f32_e32 v94, v94
	v_rcp_f32_e32 v95, v95
	s_nop 0
	v_pk_mul_f32 v[92:93], v[92:93], v[94:95]
	s_nop 0
	v_cvt_pk_bf16_f32 v92, v92, v93
	v_mul_f32_e32 v93, 0xbfb8aa3b, v78
	v_exp_f32_e32 v93, v93
	s_nop 0
	v_add_f32_e32 v93, 1.0, v93
	v_rcp_f32_e32 v94, v93
	v_mul_f32_e32 v93, 0xbfb8aa3b, v79
	v_exp_f32_e32 v93, v93
	s_nop 0
	v_add_f32_e32 v93, 1.0, v93
	v_rcp_f32_e32 v95, v93
	s_nop 0
	v_pk_mul_f32 v[78:79], v[78:79], v[94:95]
	s_nop 0
	v_cvt_pk_bf16_f32 v93, v78, v79
	ds_write_b64 v102, v[92:93] offset:528
	s_cbranch_scc0 .LBB0_540
	v_mad_u32_u24 v66, v83, s79, 0
	v_and_b32_e32 v67, 48, v1
	v_add_u32_e32 v67, v66, v67
	s_waitcnt lgkmcnt(0)
	s_barrier
	ds_read_b128 v[68:71], v67
	ds_read_b128 v[88:91], v67 offset:8448
	ds_read_b128 v[96:99], v67 offset:16896
	ds_read_b128 v[104:107], v67 offset:25344
	s_waitcnt lgkmcnt(3)
	v_mfma_f32_16x16x32_bf16 v[84:87], v[58:61], v[68:71], 0
	s_movk_i32 s0, 0xffc0
	v_mfma_f32_16x16x32_bf16 v[68:71], v[62:65], v[68:71], 0
	s_waitcnt lgkmcnt(2)
	v_mfma_f32_16x16x32_bf16 v[92:95], v[58:61], v[88:91], 0
	v_mfma_f32_16x16x32_bf16 v[88:91], v[62:65], v[88:91], 0
	s_waitcnt lgkmcnt(1)
	v_mfma_f32_16x16x32_bf16 v[100:103], v[58:61], v[96:99], 0
	v_mfma_f32_16x16x32_bf16 v[96:99], v[62:65], v[96:99], 0
	s_waitcnt lgkmcnt(0)
	ds_read_b128 v[120:123], v67 offset:64
	ds_read_b128 v[124:127], v67 offset:8512
	ds_read_b128 v[128:131], v67 offset:16960
	v_mfma_f32_16x16x32_bf16 v[58:61], v[58:61], v[104:107], 0
	v_mfma_f32_16x16x32_bf16 v[62:65], v[62:65], v[104:107], 0
	s_nop 0
	s_waitcnt lgkmcnt(2)
	v_mfma_f32_16x16x32_bf16 v[84:87], v[50:53], v[120:123], v[84:87]
	v_mfma_f32_16x16x32_bf16 v[68:71], v[54:57], v[120:123], v[68:71]
	s_nop 0
	ds_read_b128 v[120:123], v67 offset:128
	s_waitcnt lgkmcnt(2)
	v_mfma_f32_16x16x32_bf16 v[92:95], v[50:53], v[124:127], v[92:95]
	v_mfma_f32_16x16x32_bf16 v[88:91], v[54:57], v[124:127], v[88:91]
	s_nop 0
	ds_read_b128 v[124:127], v67 offset:8576
	s_waitcnt lgkmcnt(2)
	v_mfma_f32_16x16x32_bf16 v[100:103], v[50:53], v[128:131], v[100:103]
	v_mfma_f32_16x16x32_bf16 v[96:99], v[54:57], v[128:131], v[96:99]
	ds_read_b128 v[104:107], v67 offset:25408
	ds_read_b128 v[128:131], v67 offset:17024
	s_waitcnt lgkmcnt(1)
	v_mfma_f32_16x16x32_bf16 v[50:53], v[50:53], v[104:107], v[58:61]
	s_nop 2
	s_nop 0
	v_mfma_f32_16x16x32_bf16 v[54:57], v[54:57], v[104:107], v[62:65]
	s_waitcnt lgkmcnt(1)
	v_mfma_f32_16x16x32_bf16 v[62:65], v[42:45], v[120:123], v[84:87]
	v_mfma_f32_16x16x32_bf16 v[58:61], v[46:49], v[120:123], v[68:71]
	s_nop 2
	s_nop 0
	ds_read_b128 v[120:123], v67 offset:192
	s_waitcnt lgkmcnt(2)
	v_mfma_f32_16x16x32_bf16 v[84:87], v[42:45], v[124:127], v[92:95]
	v_mfma_f32_16x16x32_bf16 v[68:71], v[46:49], v[124:127], v[88:91]
	s_nop 2
	s_nop 0
	ds_read_b128 v[124:127], v67 offset:8640
	s_waitcnt lgkmcnt(2)
	v_mfma_f32_16x16x32_bf16 v[92:95], v[42:45], v[128:131], v[100:103]
	v_mfma_f32_16x16x32_bf16 v[88:91], v[46:49], v[128:131], v[96:99]
	s_nop 2
	ds_read_b128 v[96:99], v67 offset:25472
	ds_read_b128 v[128:131], v67 offset:17088
	s_waitcnt lgkmcnt(1)
	v_mfma_f32_16x16x32_bf16 v[42:45], v[42:45], v[96:99], v[50:53]
	s_nop 2
	s_nop 0
	v_mfma_f32_16x16x32_bf16 v[46:49], v[46:49], v[96:99], v[54:57]
	s_waitcnt lgkmcnt(1)
	v_mfma_f32_16x16x32_bf16 v[54:57], v[34:37], v[120:123], v[62:65]
	v_mfma_f32_16x16x32_bf16 v[50:53], v[38:41], v[120:123], v[58:61]
	s_nop 2
	s_nop 0
	ds_read_b128 v[120:123], v67 offset:256
	s_waitcnt lgkmcnt(2)
	v_mfma_f32_16x16x32_bf16 v[62:65], v[34:37], v[124:127], v[84:87]
	v_mfma_f32_16x16x32_bf16 v[58:61], v[38:41], v[124:127], v[68:71]
	s_nop 2
	s_nop 0
	ds_read_b128 v[124:127], v67 offset:8704
	s_waitcnt lgkmcnt(2)
	v_mfma_f32_16x16x32_bf16 v[84:87], v[34:37], v[128:131], v[92:95]
	v_mfma_f32_16x16x32_bf16 v[68:71], v[38:41], v[128:131], v[88:91]
	s_nop 2
	ds_read_b128 v[88:91], v67 offset:25536
	ds_read_b128 v[128:131], v67 offset:17152
	s_waitcnt lgkmcnt(1)
	v_mfma_f32_16x16x32_bf16 v[34:37], v[34:37], v[88:91], v[42:45]
	s_nop 2
	s_nop 0
	v_mfma_f32_16x16x32_bf16 v[38:41], v[38:41], v[88:91], v[46:49]
	s_waitcnt lgkmcnt(1)
	v_mfma_f32_16x16x32_bf16 v[46:49], v[26:29], v[120:123], v[54:57]
	v_mfma_f32_16x16x32_bf16 v[42:45], v[30:33], v[120:123], v[50:53]
	s_nop 2
	s_nop 0
	ds_read_b128 v[120:123], v67 offset:320
	s_waitcnt lgkmcnt(2)
	v_mfma_f32_16x16x32_bf16 v[54:57], v[26:29], v[124:127], v[62:65]
	v_mfma_f32_16x16x32_bf16 v[50:53], v[30:33], v[124:127], v[58:61]
	s_nop 2
	s_nop 0
	ds_read_b128 v[124:127], v67 offset:8768
	s_waitcnt lgkmcnt(2)
	v_mfma_f32_16x16x32_bf16 v[62:65], v[26:29], v[128:131], v[84:87]
	v_mfma_f32_16x16x32_bf16 v[58:61], v[30:33], v[128:131], v[68:71]
	s_nop 2
	ds_read_b128 v[68:71], v67 offset:25600
	ds_read_b128 v[128:131], v67 offset:17216
	s_waitcnt lgkmcnt(1)
	v_mfma_f32_16x16x32_bf16 v[26:29], v[26:29], v[68:71], v[34:37]
	s_nop 2
	s_nop 0
	v_mfma_f32_16x16x32_bf16 v[30:33], v[30:33], v[68:71], v[38:41]
	s_waitcnt lgkmcnt(1)
	v_mfma_f32_16x16x32_bf16 v[38:41], v[18:21], v[120:123], v[46:49]
	v_mfma_f32_16x16x32_bf16 v[34:37], v[22:25], v[120:123], v[42:45]
	s_nop 2
	s_nop 0
	ds_read_b128 v[120:123], v67 offset:384
	s_waitcnt lgkmcnt(2)
	v_mfma_f32_16x16x32_bf16 v[46:49], v[18:21], v[124:127], v[54:57]
	v_mfma_f32_16x16x32_bf16 v[42:45], v[22:25], v[124:127], v[50:53]
	s_nop 2
	s_nop 0
	ds_read_b128 v[124:127], v67 offset:8832
	s_waitcnt lgkmcnt(2)
	v_mfma_f32_16x16x32_bf16 v[54:57], v[18:21], v[128:131], v[62:65]
	v_mfma_f32_16x16x32_bf16 v[50:53], v[22:25], v[128:131], v[58:61]
	s_nop 2
	ds_read_b128 v[58:61], v67 offset:25664
	ds_read_b128 v[128:131], v67 offset:17280
	s_waitcnt lgkmcnt(1)
	v_mfma_f32_16x16x32_bf16 v[18:21], v[18:21], v[58:61], v[26:29]
	s_nop 2
	s_nop 0
	v_mfma_f32_16x16x32_bf16 v[22:25], v[22:25], v[58:61], v[30:33]
	s_waitcnt lgkmcnt(1)
	v_mfma_f32_16x16x32_bf16 v[30:33], v[10:13], v[120:123], v[38:41]
	v_mfma_f32_16x16x32_bf16 v[26:29], v[14:17], v[120:123], v[34:37]
	s_nop 2
	s_nop 0
	ds_read_b128 v[120:123], v67 offset:448
	s_waitcnt lgkmcnt(2)
	v_mfma_f32_16x16x32_bf16 v[38:41], v[10:13], v[124:127], v[46:49]
	v_mfma_f32_16x16x32_bf16 v[34:37], v[14:17], v[124:127], v[42:45]
	s_nop 2
	s_nop 0
	ds_read_b128 v[124:127], v67 offset:8896
	s_waitcnt lgkmcnt(2)
	v_mfma_f32_16x16x32_bf16 v[46:49], v[10:13], v[128:131], v[54:57]
	v_mfma_f32_16x16x32_bf16 v[42:45], v[14:17], v[128:131], v[50:53]
	s_nop 2
	ds_read_b128 v[50:53], v67 offset:25728
	ds_read_b128 v[128:131], v67 offset:17344
	s_waitcnt lgkmcnt(1)
	v_mfma_f32_16x16x32_bf16 v[10:13], v[10:13], v[50:53], v[18:21]
	s_nop 2
	s_nop 0
	v_mfma_f32_16x16x32_bf16 v[14:17], v[14:17], v[50:53], v[22:25]
	s_waitcnt lgkmcnt(1)
	v_mfma_f32_16x16x32_bf16 v[22:25], v[2:5], v[120:123], v[30:33]
	v_mfma_f32_16x16x32_bf16 v[18:21], v[6:9], v[120:123], v[26:29]
	s_nop 2
	s_nop 0
	s_waitcnt lgkmcnt(1)
	v_mfma_f32_16x16x32_bf16 v[30:33], v[2:5], v[124:127], v[38:41]
	v_mfma_f32_16x16x32_bf16 v[26:29], v[6:9], v[124:127], v[34:37]
	s_nop 2
	s_nop 0
	s_waitcnt lgkmcnt(0)
	v_mfma_f32_16x16x32_bf16 v[38:41], v[2:5], v[128:131], v[46:49]
	v_mfma_f32_16x16x32_bf16 v[34:37], v[6:9], v[128:131], v[42:45]
	s_nop 2
	ds_read_b128 v[42:45], v67 offset:25792
	s_waitcnt lgkmcnt(0)
	v_mfma_f32_16x16x32_bf16 v[2:5], v[2:5], v[42:45], v[10:13]
	s_nop 2
	v_and_or_b32 v12, v1, s0, v75
	v_cvt_pk_bf16_f32 v10, v22, v23
	v_cvt_pk_bf16_f32 v11, v24, v25
	v_mfma_f32_16x16x32_bf16 v[6:9], v[6:9], v[42:45], v[14:17]
	v_cvt_pk_bf16_f32 v13, v20, v21
	v_cvt_pk_bf16_f32 v2, v2, v3
	v_cvt_pk_bf16_f32 v3, v4, v5
	v_add_u32_e32 v14, v66, v12
	v_add_u32_e32 v15, 0xc000, v14
	v_cvt_pk_bf16_f32 v12, v18, v19
	s_nop 1
	v_cvt_pk_bf16_f32 v4, v6, v7
	v_cvt_pk_bf16_f32 v5, v8, v9
	v_add_u32_e32 v6, 0x6000, v15
	ds_write2_b64 v15, v[10:11], v[12:13] offset1:4
	v_cvt_pk_bf16_f32 v10, v30, v31
	v_cvt_pk_bf16_f32 v11, v32, v33
	v_cvt_pk_bf16_f32 v12, v26, v27
	v_cvt_pk_bf16_f32 v13, v28, v29
	v_add_u32_e32 v14, 0xe000, v14
	ds_write2_b64 v6, v[2:3], v[4:5] offset0:96 offset1:100
	v_mov_b32_e32 v75, v0
	v_add_u32_e32 v4, s13, v77
	ds_write2_b64 v14, v[10:11], v[12:13] offset0:32 offset1:36
	v_cvt_pk_bf16_f32 v10, v38, v39
	v_cvt_pk_bf16_f32 v11, v40, v41
	v_cvt_pk_bf16_f32 v12, v34, v35
	v_cvt_pk_bf16_f32 v13, v36, v37
	v_add_u32_e32 v14, 0x4000, v15
	v_lshl_add_u64 v[2:3], s[56:57], 0, v[74:75]
	v_cmp_gt_i32_e32 vcc, s75, v4
	ds_write2_b64 v14, v[10:11], v[12:13] offset0:64 offset1:68
	s_waitcnt lgkmcnt(0)
	s_barrier
	s_and_saveexec_b64 s[0:1], vcc
	s_cbranch_execz .LBB0_543
	v_mad_u64_u32 v[6:7], s[36:37], v77, s79, v[76:77]
	v_mov_b32_e32 v5, s7
	v_mov_b32_e32 v10, s12
	v_cmp_gt_i32_e32 vcc, 16, v4
	ds_read_b128 v[6:9], v6 offset:49152
	s_nop 0
	v_cndmask_b32_e32 v5, v5, v10, vcc
	v_add_u32_e32 v4, v5, v4
	v_ashrrev_i32_e32 v5, 31, v4
	v_lshlrev_b64 v[4:5], 11, v[4:5]
	v_lshl_add_u64 v[4:5], v[2:3], 0, v[4:5]
	s_waitcnt lgkmcnt(0)
	global_store_dwordx4 v[4:5], v[6:9], off
